# RMSNorm phase in two overlapped halves (first half's stores overlap second half's loads), DPP+permlane wave reductions
# baseline (speedup 1.0000x reference)
; __device__ __forceinline__ void norm_mod_phase(const float* X, const float* ng, const float* mod, bf16* H, int G) {
;     int tid = threadIdx.x; asm volatile("" : "+v"(tid)); const int lane = tid & 63, wave = tid >> 6;
;     const int gw = blockIdx.x * NWAVES + wave, NGW = G * NWAVES;
; #pragma unroll 1
;     for (int b = 0; b < 2; ++b) {
;         f32x4 gs[4], sh[4];
; #pragma unroll
;         for (int j = 0; j < 4; ++j) { const int c = 4 * lane + 256 * j; gs[j] = *(const f32x4*)(ng + c) * (*(const f32x4*)(mod + b * 3072 + 1024 + c) + 1.0f); sh[j] = *(const f32x4*)(mod + b * 3072 + c); }
;         for (int tb = gw; tb < SEQL; tb += 4 * NGW) {
;             f32x4 v[4][4]; float s[4]; int mr[4]; bool has[4];
; #pragma unroll
;             for (int r = 0; r < 4; ++r) { const int t = tb + r * NGW; has[r] = t < SEQL; mr[r] = b * SEQL + (has[r] ? t : tb); const f32x4* xr = (const f32x4*)(X + (size_t)mr[r] * D) + lane;
; #pragma unroll
;                 for (int j = 0; j < 4; ++j) v[r][j] = xr[64 * j]; }
.LBB0_85:
	s_or_b64 exec, exec, s[12:13]
	s_waitcnt lgkmcnt(0)
	v_mov_b32_e32 v0, v216
	s_barrier
	s_add_u32 s12, s10, 0x1800000
	v_and_b32_e32 v1, 63, v0
	v_ashrrev_i32_e32 v0, 6, v0
	v_readlane_b32 s3, v249, 3
	v_mov_b32_e32 v3, 0
	s_addc_u32 s13, s11, 0
	v_add_u32_e32 v110, s3, v0
	v_lshlrev_b32_e32 v0, 2, v1
	v_lshlrev_b32_e32 v2, 4, v1
	v_lshlrev_b32_e32 v4, 3, v1
	v_mov_b32_e32 v5, v3
	v_lshl_add_u64 v[80:81], s[68:69], 0, v[2:3]
	v_lshl_add_u64 v[82:83], s[12:13], 0, v[4:5]
	v_lshl_add_u64 v[84:85], s[72:73], 0, v[2:3]
	v_or_b32_e32 v2, 0x100, v0
	v_or_b32_e32 v4, 0x200, v0
	v_or_b32_e32 v6, 0x300, v0
	v_lshlrev_b32_e32 v111, 2, v0
	v_mbcnt_lo_u32_b32 v0, -1, 0
	v_mbcnt_hi_u32_b32 v208, -1, v0
	s_movk_i32 s3, 0x2000
	s_add_i32 s7, s4, s4
	v_and_b32_e32 v217, 64, v208
	v_cmp_gt_i32_e64 s[36:37], s3, v110
	s_lshl_b32 s5, s6, 4
	s_mov_b32 s21, 0
	s_mov_b64 s[22:23], -1
	v_lshlrev_b32_e32 v112, 2, v2
	v_lshlrev_b32_e32 v113, 2, v4
	v_lshlrev_b32_e32 v114, 2, v6
	v_mov_b32_e32 v115, 0x358637bd
	s_add_i32 s7, s7, s4
	v_add_u32_e32 v209, 64, v217
	v_xor_b32_e32 v215, 1, v208
	v_xor_b32_e32 v214, 2, v208
	v_xor_b32_e32 v213, 4, v208
	v_xor_b32_e32 v212, 8, v208
	v_xor_b32_e32 v211, 16, v208
	v_xor_b32_e32 v210, 32, v208
	s_cmp_eq_u32 s6, 0x100
	s_cbranch_scc0 .Lnorm_orig
	v_lshlrev_b32_e32 v107, 4, v208
	v_lshlrev_b32_e32 v106, 3, v208
	v_readfirstlane_b32 s16, v110
	s_lshl_b32 s14, s6, 3
	s_add_u32 s38, s0, 0x1000
	s_addc_u32 s39, s1, 0
	s_add_u32 s40, s0, 0x3000
	s_addc_u32 s41, s1, 0
	s_add_u32 s42, s0, 0x4000
	s_addc_u32 s43, s1, 0
	global_load_dwordx4 v[0:3], v107, s[72:73]
	global_load_dwordx4 v[4:7], v107, s[72:73] offset:1024
	global_load_dwordx4 v[8:11], v107, s[72:73] offset:2048
	global_load_dwordx4 v[12:15], v107, s[72:73] offset:3072
	global_load_dwordx4 v[16:19], v107, s[38:39]
	global_load_dwordx4 v[20:23], v107, s[38:39] offset:1024
	global_load_dwordx4 v[24:27], v107, s[38:39] offset:2048
	global_load_dwordx4 v[28:31], v107, s[38:39] offset:3072
	global_load_dwordx4 v[32:35], v107, s[0:1]
	global_load_dwordx4 v[36:39], v107, s[0:1] offset:1024
	global_load_dwordx4 v[40:43], v107, s[0:1] offset:2048
	global_load_dwordx4 v[44:47], v107, s[0:1] offset:3072
	global_load_dwordx4 v[48:51], v107, s[42:43]
	global_load_dwordx4 v[52:55], v107, s[42:43] offset:1024
	global_load_dwordx4 v[56:59], v107, s[42:43] offset:2048
	global_load_dwordx4 v[60:63], v107, s[42:43] offset:3072
	global_load_dwordx4 v[64:67], v107, s[40:41]
	global_load_dwordx4 v[68:71], v107, s[40:41] offset:1024
	global_load_dwordx4 v[72:75], v107, s[40:41] offset:2048
	global_load_dwordx4 v[76:79], v107, s[40:41] offset:3072
	s_mov_b32 s18, s16
	s_lshl_b32 s20, s18, 12
	s_add_u32 s22, s68, s20
	s_addc_u32 s23, s69, 0
	global_load_dwordx4 v[116:119], v107, s[22:23]
	global_load_dwordx4 v[120:123], v107, s[22:23] offset:1024
	global_load_dwordx4 v[124:127], v107, s[22:23] offset:2048
	global_load_dwordx4 v[128:131], v107, s[22:23] offset:3072
	s_add_i32 s18, s18, s14
	s_lshl_b32 s20, s18, 12
	s_add_u32 s22, s68, s20
	s_addc_u32 s23, s69, 0
	global_load_dwordx4 v[132:135], v107, s[22:23]
	global_load_dwordx4 v[136:139], v107, s[22:23] offset:1024
	global_load_dwordx4 v[140:143], v107, s[22:23] offset:2048
	global_load_dwordx4 v[144:147], v107, s[22:23] offset:3072
	s_add_i32 s18, s18, s14
	s_lshl_b32 s20, s18, 12
	s_add_u32 s22, s68, s20
	s_addc_u32 s23, s69, 0
	global_load_dwordx4 v[148:151], v107, s[22:23]
	global_load_dwordx4 v[152:155], v107, s[22:23] offset:1024
	global_load_dwordx4 v[156:159], v107, s[22:23] offset:2048
	global_load_dwordx4 v[160:163], v107, s[22:23] offset:3072
	s_add_i32 s18, s18, s14
	s_lshl_b32 s20, s18, 12
	s_add_u32 s22, s68, s20
	s_addc_u32 s23, s69, 0
	global_load_dwordx4 v[164:167], v107, s[22:23]
	global_load_dwordx4 v[168:171], v107, s[22:23] offset:1024
	global_load_dwordx4 v[172:175], v107, s[22:23] offset:2048
	global_load_dwordx4 v[176:179], v107, s[22:23] offset:3072
	s_add_i32 s18, s16, 8192
	s_lshl_b32 s20, s18, 12
	s_add_u32 s22, s68, s20
	s_addc_u32 s23, s69, 0
	global_load_dwordx4 v[180:183], v107, s[22:23]
	global_load_dwordx4 v[184:187], v107, s[22:23] offset:1024
	global_load_dwordx4 v[188:191], v107, s[22:23] offset:2048
	global_load_dwordx4 v[192:195], v107, s[22:23] offset:3072
	s_add_i32 s18, s18, s14
	s_lshl_b32 s20, s18, 12
	s_add_u32 s22, s68, s20
	s_addc_u32 s23, s69, 0
	global_load_dwordx4 v[86:89], v107, s[22:23]
	global_load_dwordx4 v[90:93], v107, s[22:23] offset:1024
	global_load_dwordx4 v[94:97], v107, s[22:23] offset:2048
	global_load_dwordx4 v[98:101], v107, s[22:23] offset:3072
	s_add_i32 s18, s18, s14
	s_lshl_b32 s20, s18, 12
	s_add_u32 s22, s68, s20
	s_addc_u32 s23, s69, 0
	global_load_dwordx4 v[218:221], v107, s[22:23]
	global_load_dwordx4 v[222:225], v107, s[22:23] offset:1024
	global_load_dwordx4 v[226:229], v107, s[22:23] offset:2048
	global_load_dwordx4 v[230:233], v107, s[22:23] offset:3072
	s_add_i32 s18, s18, s14
	s_lshl_b32 s20, s18, 12
	s_add_u32 s22, s68, s20
	s_addc_u32 s23, s69, 0
	global_load_dwordx4 v[196:199], v107, s[22:23]
	global_load_dwordx4 v[200:203], v107, s[22:23] offset:1024
	global_load_dwordx4 v[204:207], v107, s[22:23] offset:2048
	global_load_dwordx4 v[102:105], v107, s[22:23] offset:3072
	v_xor_b32_e32 v242, 1, v208
	v_lshlrev_b32_e32 v242, 2, v242
	v_xor_b32_e32 v243, 2, v208
	v_lshlrev_b32_e32 v243, 2, v243
	v_xor_b32_e32 v244, 4, v208
	v_lshlrev_b32_e32 v244, 2, v244
	v_xor_b32_e32 v245, 8, v208
	v_lshlrev_b32_e32 v245, 2, v245
	v_xor_b32_e32 v246, 16, v208
	v_lshlrev_b32_e32 v246, 2, v246
	v_xor_b32_e32 v247, 32, v208
	v_lshlrev_b32_e32 v247, 2, v247
	v_mov_b32_e32 v108, 0x358637bd
	s_waitcnt vmcnt(32)
; __device__ __forceinline__ void norm_mod_phase(const float* X, const float* ng, const float* mod, bf16* H, int G) {
;     ...
;         for (int j = 0; j < 4; ++j) { const int c = 4 * lane + 256 * j; gs[j] = *(const f32x4*)(ng + c) * (*(const f32x4*)(mod + b * 3072 + 1024 + c) + 1.0f); sh[j] = *(const f32x4*)(mod + b * 3072 + c); }
;         for (int tb = gw; tb < SEQL; tb += 4 * NGW) {
;             f32x4 v[4][4]; float s[4]; int mr[4]; bool has[4];
; #pragma unroll
;             for (int r = 0; r < 4; ++r) { const int t = tb + r * NGW; has[r] = t < SEQL; mr[r] = b * SEQL + (has[r] ? t : tb); const f32x4* xr = (const f32x4*)(X + (size_t)mr[r] * D) + lane;
; #pragma unroll
;                 for (int j = 0; j < 4; ++j) v[r][j] = xr[64 * j]; }
; #pragma unroll
;             for (int r = 0; r < 4; ++r) { float q = 0.f;
; #pragma unroll
;                 for (int j = 0; j < 4; ++j) q += (v[r][j].x * v[r][j].x + v[r][j].y * v[r][j].y) + (v[r][j].z * v[r][j].z + v[r][j].w * v[r][j].w);
;                 s[r] = q; }
; #pragma unroll
;             for (int o = 1; o < 64; o <<= 1) {
; #pragma unroll
;                 for (int r = 0; r < 4; ++r) s[r] += __shfl_xor(s[r], o); }
	v_add_f32_e32 v16, 1.0, v16
	v_add_f32_e32 v17, 1.0, v17
	v_add_f32_e32 v18, 1.0, v18
	v_add_f32_e32 v19, 1.0, v19
	v_add_f32_e32 v20, 1.0, v20
	v_add_f32_e32 v21, 1.0, v21
	v_add_f32_e32 v22, 1.0, v22
	v_add_f32_e32 v23, 1.0, v23
	v_add_f32_e32 v24, 1.0, v24
	v_add_f32_e32 v25, 1.0, v25
	v_add_f32_e32 v26, 1.0, v26
	v_add_f32_e32 v27, 1.0, v27
	v_add_f32_e32 v28, 1.0, v28
	v_add_f32_e32 v29, 1.0, v29
	v_add_f32_e32 v30, 1.0, v30
	v_add_f32_e32 v31, 1.0, v31
	v_mul_f32_e32 v16, v0, v16
	v_mul_f32_e32 v17, v1, v17
	v_mul_f32_e32 v18, v2, v18
	v_mul_f32_e32 v19, v3, v19
	v_mul_f32_e32 v20, v4, v20
	v_mul_f32_e32 v21, v5, v21
	v_mul_f32_e32 v22, v6, v22
	v_mul_f32_e32 v23, v7, v23
	v_mul_f32_e32 v24, v8, v24
	v_mul_f32_e32 v25, v9, v25
	v_mul_f32_e32 v26, v10, v26
	v_mul_f32_e32 v27, v11, v27
	v_mul_f32_e32 v28, v12, v28
	v_mul_f32_e32 v29, v13, v29
	v_mul_f32_e32 v30, v14, v30
	v_mul_f32_e32 v31, v15, v31
	v_add_f32_e32 v48, 1.0, v48
	v_add_f32_e32 v49, 1.0, v49
	v_add_f32_e32 v50, 1.0, v50
	v_add_f32_e32 v51, 1.0, v51
	v_add_f32_e32 v52, 1.0, v52
	v_add_f32_e32 v53, 1.0, v53
	v_add_f32_e32 v54, 1.0, v54
	v_add_f32_e32 v55, 1.0, v55
	v_add_f32_e32 v56, 1.0, v56
	v_add_f32_e32 v57, 1.0, v57
	v_add_f32_e32 v58, 1.0, v58
	v_add_f32_e32 v59, 1.0, v59
	v_add_f32_e32 v60, 1.0, v60
	v_add_f32_e32 v61, 1.0, v61
	v_add_f32_e32 v62, 1.0, v62
	v_add_f32_e32 v63, 1.0, v63
	v_mul_f32_e32 v48, v0, v48
	v_mul_f32_e32 v49, v1, v49
	v_mul_f32_e32 v50, v2, v50
	v_mul_f32_e32 v51, v3, v51
	v_mul_f32_e32 v52, v4, v52
	v_mul_f32_e32 v53, v5, v53
	v_mul_f32_e32 v54, v6, v54
	v_mul_f32_e32 v55, v7, v55
	v_mul_f32_e32 v56, v8, v56
	v_mul_f32_e32 v57, v9, v57
	v_mul_f32_e32 v58, v10, v58
	v_mul_f32_e32 v59, v11, v59
	v_mul_f32_e32 v60, v12, v60
	v_mul_f32_e32 v61, v13, v61
	v_mul_f32_e32 v62, v14, v62
	v_mul_f32_e32 v63, v15, v63
	s_waitcnt vmcnt(28)
	v_mul_f32_e32 v250, v116, v116
	v_mul_f32_e32 v251, v118, v118
	v_fmac_f32_e32 v250, v117, v117
	v_fmac_f32_e32 v251, v119, v119
	v_add_f32_e32 v234, v250, v251
	v_mul_f32_e32 v250, v120, v120
	v_mul_f32_e32 v251, v122, v122
	v_fmac_f32_e32 v250, v121, v121
	v_fmac_f32_e32 v251, v123, v123
	v_add_f32_e32 v250, v250, v251
	v_add_f32_e32 v234, v234, v250
	v_mul_f32_e32 v250, v124, v124
	v_mul_f32_e32 v251, v126, v126
	v_fmac_f32_e32 v250, v125, v125
	v_fmac_f32_e32 v251, v127, v127
	v_add_f32_e32 v250, v250, v251
	v_add_f32_e32 v234, v234, v250
	v_mul_f32_e32 v250, v128, v128
	v_mul_f32_e32 v251, v130, v130
	v_fmac_f32_e32 v250, v129, v129
	v_fmac_f32_e32 v251, v131, v131
	v_add_f32_e32 v250, v250, v251
	v_add_f32_e32 v234, v234, v250
	s_waitcnt vmcnt(24)
	v_mul_f32_e32 v250, v132, v132
	v_mul_f32_e32 v251, v134, v134
	v_fmac_f32_e32 v250, v133, v133
	v_fmac_f32_e32 v251, v135, v135
	v_add_f32_e32 v235, v250, v251
	v_mul_f32_e32 v250, v136, v136
	v_mul_f32_e32 v251, v138, v138
	v_fmac_f32_e32 v250, v137, v137
	v_fmac_f32_e32 v251, v139, v139
	v_add_f32_e32 v250, v250, v251
	v_add_f32_e32 v235, v235, v250
	v_mul_f32_e32 v250, v140, v140
	v_mul_f32_e32 v251, v142, v142
	v_fmac_f32_e32 v250, v141, v141
	v_fmac_f32_e32 v251, v143, v143
	v_add_f32_e32 v250, v250, v251
	v_add_f32_e32 v235, v235, v250
	v_mul_f32_e32 v250, v144, v144
	v_mul_f32_e32 v251, v146, v146
	v_fmac_f32_e32 v250, v145, v145
	v_fmac_f32_e32 v251, v147, v147
	v_add_f32_e32 v250, v250, v251
	v_add_f32_e32 v235, v235, v250
	s_waitcnt vmcnt(20)
	v_mul_f32_e32 v250, v148, v148
	v_mul_f32_e32 v251, v150, v150
	v_fmac_f32_e32 v250, v149, v149
	v_fmac_f32_e32 v251, v151, v151
	v_add_f32_e32 v236, v250, v251
	v_mul_f32_e32 v250, v152, v152
	v_mul_f32_e32 v251, v154, v154
	v_fmac_f32_e32 v250, v153, v153
	v_fmac_f32_e32 v251, v155, v155
	v_add_f32_e32 v250, v250, v251
	v_add_f32_e32 v236, v236, v250
	v_mul_f32_e32 v250, v156, v156
	v_mul_f32_e32 v251, v158, v158
	v_fmac_f32_e32 v250, v157, v157
	v_fmac_f32_e32 v251, v159, v159
	v_add_f32_e32 v250, v250, v251
	v_add_f32_e32 v236, v236, v250
	v_mul_f32_e32 v250, v160, v160
	v_mul_f32_e32 v251, v162, v162
	v_fmac_f32_e32 v250, v161, v161
	v_fmac_f32_e32 v251, v163, v163
	v_add_f32_e32 v250, v250, v251
	v_add_f32_e32 v236, v236, v250
	s_waitcnt vmcnt(16)
	v_mul_f32_e32 v250, v164, v164
	v_mul_f32_e32 v251, v166, v166
	v_fmac_f32_e32 v250, v165, v165
	v_fmac_f32_e32 v251, v167, v167
	v_add_f32_e32 v237, v250, v251
	v_mul_f32_e32 v250, v168, v168
	v_mul_f32_e32 v251, v170, v170
	v_fmac_f32_e32 v250, v169, v169
	v_fmac_f32_e32 v251, v171, v171
	v_add_f32_e32 v250, v250, v251
	v_add_f32_e32 v237, v237, v250
	v_mul_f32_e32 v250, v172, v172
	v_mul_f32_e32 v251, v174, v174
	v_fmac_f32_e32 v250, v173, v173
	v_fmac_f32_e32 v251, v175, v175
	v_add_f32_e32 v250, v250, v251
	v_add_f32_e32 v237, v237, v250
	v_mul_f32_e32 v250, v176, v176
	v_mul_f32_e32 v251, v178, v178
	v_fmac_f32_e32 v250, v177, v177
	v_fmac_f32_e32 v251, v179, v179
	v_add_f32_e32 v250, v250, v251
	v_add_f32_e32 v237, v237, v250
	s_nop 1
	v_add_f32_dpp v234, v234, v234 quad_perm:[1,0,3,2] row_mask:0xf bank_mask:0xf
	v_add_f32_dpp v235, v235, v235 quad_perm:[1,0,3,2] row_mask:0xf bank_mask:0xf
	v_add_f32_dpp v236, v236, v236 quad_perm:[1,0,3,2] row_mask:0xf bank_mask:0xf
	v_add_f32_dpp v237, v237, v237 quad_perm:[1,0,3,2] row_mask:0xf bank_mask:0xf
	v_add_f32_dpp v234, v234, v234 quad_perm:[2,3,0,1] row_mask:0xf bank_mask:0xf
	v_add_f32_dpp v235, v235, v235 quad_perm:[2,3,0,1] row_mask:0xf bank_mask:0xf
	v_add_f32_dpp v236, v236, v236 quad_perm:[2,3,0,1] row_mask:0xf bank_mask:0xf
	v_add_f32_dpp v237, v237, v237 quad_perm:[2,3,0,1] row_mask:0xf bank_mask:0xf
	v_add_f32_dpp v234, v234, v234 row_half_mirror row_mask:0xf bank_mask:0xf
; __device__ __forceinline__ unsigned pk2(float lo, float hi) { f32x2_t v = {lo, hi}; bf16x2_t b = __builtin_convertvector(v, bf16x2_t); return __builtin_bit_cast(unsigned, b); }
; __device__ __forceinline__ void norm_mod_phase(const float* X, const float* ng, const float* mod, bf16* H, int G) {
;     ...
;             for (int o = 1; o < 64; o <<= 1) {
; #pragma unroll
;                 for (int r = 0; r < 4; ++r) s[r] += __shfl_xor(s[r], o); }
; #pragma unroll
;             for (int r = 0; r < 4; ++r) { if (!has[r]) continue;
;                 const float rs = __builtin_amdgcn_rsqf(s[r] * (1.f / D) + EPSN); v2u* o8 = (v2u*)(H + (size_t)mr[r] * D) + lane;
; #pragma unroll
;                 for (int j = 0; j < 4; ++j) { const f32x4 h = v[r][j] * rs * gs[j] + sh[j]; o8[64 * j] = (v2u){pk2(h.x, h.y), pk2(h.z, h.w)}; } }
	v_add_f32_dpp v235, v235, v235 row_half_mirror row_mask:0xf bank_mask:0xf
	v_add_f32_dpp v236, v236, v236 row_half_mirror row_mask:0xf bank_mask:0xf
	v_add_f32_dpp v237, v237, v237 row_half_mirror row_mask:0xf bank_mask:0xf
	v_add_f32_dpp v234, v234, v234 row_mirror row_mask:0xf bank_mask:0xf
	v_add_f32_dpp v235, v235, v235 row_mirror row_mask:0xf bank_mask:0xf
	v_add_f32_dpp v236, v236, v236 row_mirror row_mask:0xf bank_mask:0xf
	v_add_f32_dpp v237, v237, v237 row_mirror row_mask:0xf bank_mask:0xf
	v_mov_b32_e32 v109, v234
	v_mov_b32_e32 v110, v235
	v_mov_b32_e32 v111, v236
	v_mov_b32_e32 v112, v237
	s_nop 1
	v_permlane16_swap_b32_e32 v109, v234
	v_permlane16_swap_b32_e32 v110, v235
	v_permlane16_swap_b32_e32 v111, v236
	v_permlane16_swap_b32_e32 v112, v237
	s_nop 1
	v_add_f32_e32 v234, v234, v109
	v_add_f32_e32 v235, v235, v110
	v_add_f32_e32 v236, v236, v111
	v_add_f32_e32 v237, v237, v112
	v_mov_b32_e32 v109, v234
	v_mov_b32_e32 v110, v235
	v_mov_b32_e32 v111, v236
	v_mov_b32_e32 v112, v237
	s_nop 1
	v_permlane32_swap_b32_e32 v109, v234
	v_permlane32_swap_b32_e32 v110, v235
	v_permlane32_swap_b32_e32 v111, v236
	v_permlane32_swap_b32_e32 v112, v237
	s_nop 1
	v_add_f32_e32 v234, v234, v109
	v_add_f32_e32 v235, v235, v110
	v_add_f32_e32 v236, v236, v111
	v_add_f32_e32 v237, v237, v112
	v_fmamk_f32 v234, v234, 0x3a800000, v108
	v_fmamk_f32 v235, v235, 0x3a800000, v108
	v_fmamk_f32 v236, v236, 0x3a800000, v108
	v_fmamk_f32 v237, v237, 0x3a800000, v108
	v_rsq_f32_e32 v234, v234
	v_rsq_f32_e32 v235, v235
	v_rsq_f32_e32 v236, v236
	v_rsq_f32_e32 v237, v237
	s_nop 0
	s_mov_b32 s18, s16
	s_lshl_b32 s20, s18, 11
	s_add_u32 s22, s12, s20
	s_addc_u32 s23, s13, 0
	v_mul_f32_e32 v116, v116, v234
	v_mul_f32_e32 v117, v117, v234
	v_mul_f32_e32 v118, v118, v234
	v_mul_f32_e32 v119, v119, v234
	v_fma_f32 v116, v116, v16, v32
	v_fma_f32 v117, v117, v17, v33
	v_fma_f32 v118, v118, v18, v34
	v_fma_f32 v119, v119, v19, v35
	v_cvt_pk_bf16_f32 v116, v116, v117
	v_cvt_pk_bf16_f32 v117, v118, v119
	global_store_dwordx2 v106, v[116:117], s[22:23]
	v_mul_f32_e32 v120, v120, v234
	v_mul_f32_e32 v121, v121, v234
	v_mul_f32_e32 v122, v122, v234
	v_mul_f32_e32 v123, v123, v234
	v_fma_f32 v120, v120, v20, v36
	v_fma_f32 v121, v121, v21, v37
	v_fma_f32 v122, v122, v22, v38
	v_fma_f32 v123, v123, v23, v39
	v_cvt_pk_bf16_f32 v120, v120, v121
	v_cvt_pk_bf16_f32 v121, v122, v123
	global_store_dwordx2 v106, v[120:121], s[22:23] offset:512
	v_mul_f32_e32 v124, v124, v234
	v_mul_f32_e32 v125, v125, v234
	v_mul_f32_e32 v126, v126, v234
	v_mul_f32_e32 v127, v127, v234
	v_fma_f32 v124, v124, v24, v40
	v_fma_f32 v125, v125, v25, v41
	v_fma_f32 v126, v126, v26, v42
	v_fma_f32 v127, v127, v27, v43
	v_cvt_pk_bf16_f32 v124, v124, v125
	v_cvt_pk_bf16_f32 v125, v126, v127
	global_store_dwordx2 v106, v[124:125], s[22:23] offset:1024
	v_mul_f32_e32 v128, v128, v234
	v_mul_f32_e32 v129, v129, v234
	v_mul_f32_e32 v130, v130, v234
	v_mul_f32_e32 v131, v131, v234
	v_fma_f32 v128, v128, v28, v44
	v_fma_f32 v129, v129, v29, v45
	v_fma_f32 v130, v130, v30, v46
	v_fma_f32 v131, v131, v31, v47
	v_cvt_pk_bf16_f32 v128, v128, v129
	v_cvt_pk_bf16_f32 v129, v130, v131
	global_store_dwordx2 v106, v[128:129], s[22:23] offset:1536
	s_add_i32 s18, s18, s14
	s_lshl_b32 s20, s18, 11
	s_add_u32 s22, s12, s20
	s_addc_u32 s23, s13, 0
	v_mul_f32_e32 v132, v132, v235
	v_mul_f32_e32 v133, v133, v235
	v_mul_f32_e32 v134, v134, v235
	v_mul_f32_e32 v135, v135, v235
	v_fma_f32 v132, v132, v16, v32
	v_fma_f32 v133, v133, v17, v33
	v_fma_f32 v134, v134, v18, v34
	v_fma_f32 v135, v135, v19, v35
	v_cvt_pk_bf16_f32 v132, v132, v133
	v_cvt_pk_bf16_f32 v133, v134, v135
	global_store_dwordx2 v106, v[132:133], s[22:23]
	v_mul_f32_e32 v136, v136, v235
	v_mul_f32_e32 v137, v137, v235
	v_mul_f32_e32 v138, v138, v235
	v_mul_f32_e32 v139, v139, v235
	v_fma_f32 v136, v136, v20, v36
	v_fma_f32 v137, v137, v21, v37
	v_fma_f32 v138, v138, v22, v38
	v_fma_f32 v139, v139, v23, v39
	v_cvt_pk_bf16_f32 v136, v136, v137
	v_cvt_pk_bf16_f32 v137, v138, v139
	global_store_dwordx2 v106, v[136:137], s[22:23] offset:512
	v_mul_f32_e32 v140, v140, v235
	v_mul_f32_e32 v141, v141, v235
	v_mul_f32_e32 v142, v142, v235
	v_mul_f32_e32 v143, v143, v235
	v_fma_f32 v140, v140, v24, v40
	v_fma_f32 v141, v141, v25, v41
	v_fma_f32 v142, v142, v26, v42
	v_fma_f32 v143, v143, v27, v43
	v_cvt_pk_bf16_f32 v140, v140, v141
	v_cvt_pk_bf16_f32 v141, v142, v143
	global_store_dwordx2 v106, v[140:141], s[22:23] offset:1024
	v_mul_f32_e32 v144, v144, v235
	v_mul_f32_e32 v145, v145, v235
	v_mul_f32_e32 v146, v146, v235
	v_mul_f32_e32 v147, v147, v235
	v_fma_f32 v144, v144, v28, v44
	v_fma_f32 v145, v145, v29, v45
	v_fma_f32 v146, v146, v30, v46
	v_fma_f32 v147, v147, v31, v47
	v_cvt_pk_bf16_f32 v144, v144, v145
	v_cvt_pk_bf16_f32 v145, v146, v147
	global_store_dwordx2 v106, v[144:145], s[22:23] offset:1536
	s_add_i32 s18, s18, s14
	s_lshl_b32 s20, s18, 11
	s_add_u32 s22, s12, s20
	s_addc_u32 s23, s13, 0
	v_mul_f32_e32 v148, v148, v236
	v_mul_f32_e32 v149, v149, v236
	v_mul_f32_e32 v150, v150, v236
	v_mul_f32_e32 v151, v151, v236
	v_fma_f32 v148, v148, v16, v32
	v_fma_f32 v149, v149, v17, v33
	v_fma_f32 v150, v150, v18, v34
	v_fma_f32 v151, v151, v19, v35
	v_cvt_pk_bf16_f32 v148, v148, v149
	v_cvt_pk_bf16_f32 v149, v150, v151
	global_store_dwordx2 v106, v[148:149], s[22:23]
	v_mul_f32_e32 v152, v152, v236
	v_mul_f32_e32 v153, v153, v236
	v_mul_f32_e32 v154, v154, v236
	v_mul_f32_e32 v155, v155, v236
	v_fma_f32 v152, v152, v20, v36
	v_fma_f32 v153, v153, v21, v37
	v_fma_f32 v154, v154, v22, v38
	v_fma_f32 v155, v155, v23, v39
	v_cvt_pk_bf16_f32 v152, v152, v153
; __device__ __forceinline__ unsigned pk2(float lo, float hi) { f32x2_t v = {lo, hi}; bf16x2_t b = __builtin_convertvector(v, bf16x2_t); return __builtin_bit_cast(unsigned, b); }
; __device__ __forceinline__ void norm_mod_phase(const float* X, const float* ng, const float* mod, bf16* H, int G) {
;     ...
;             for (int r = 0; r < 4; ++r) { float q = 0.f;
; #pragma unroll
;                 for (int j = 0; j < 4; ++j) q += (v[r][j].x * v[r][j].x + v[r][j].y * v[r][j].y) + (v[r][j].z * v[r][j].z + v[r][j].w * v[r][j].w);
;                 s[r] = q; }
; #pragma unroll
;             for (int o = 1; o < 64; o <<= 1) {
; #pragma unroll
;                 for (int r = 0; r < 4; ++r) s[r] += __shfl_xor(s[r], o); }
; #pragma unroll
;             for (int r = 0; r < 4; ++r) { if (!has[r]) continue;
;                 const float rs = __builtin_amdgcn_rsqf(s[r] * (1.f / D) + EPSN); v2u* o8 = (v2u*)(H + (size_t)mr[r] * D) + lane;
; #pragma unroll
;                 for (int j = 0; j < 4; ++j) { const f32x4 h = v[r][j] * rs * gs[j] + sh[j]; o8[64 * j] = (v2u){pk2(h.x, h.y), pk2(h.z, h.w)}; } }
	v_cvt_pk_bf16_f32 v153, v154, v155
	global_store_dwordx2 v106, v[152:153], s[22:23] offset:512
	v_mul_f32_e32 v156, v156, v236
	v_mul_f32_e32 v157, v157, v236
	v_mul_f32_e32 v158, v158, v236
	v_mul_f32_e32 v159, v159, v236
	v_fma_f32 v156, v156, v24, v40
	v_fma_f32 v157, v157, v25, v41
	v_fma_f32 v158, v158, v26, v42
	v_fma_f32 v159, v159, v27, v43
	v_cvt_pk_bf16_f32 v156, v156, v157
	v_cvt_pk_bf16_f32 v157, v158, v159
	global_store_dwordx2 v106, v[156:157], s[22:23] offset:1024
	v_mul_f32_e32 v160, v160, v236
	v_mul_f32_e32 v161, v161, v236
	v_mul_f32_e32 v162, v162, v236
	v_mul_f32_e32 v163, v163, v236
	v_fma_f32 v160, v160, v28, v44
	v_fma_f32 v161, v161, v29, v45
	v_fma_f32 v162, v162, v30, v46
	v_fma_f32 v163, v163, v31, v47
	v_cvt_pk_bf16_f32 v160, v160, v161
	v_cvt_pk_bf16_f32 v161, v162, v163
	global_store_dwordx2 v106, v[160:161], s[22:23] offset:1536
	s_add_i32 s18, s18, s14
	s_lshl_b32 s20, s18, 11
	s_add_u32 s22, s12, s20
	s_addc_u32 s23, s13, 0
	v_mul_f32_e32 v164, v164, v237
	v_mul_f32_e32 v165, v165, v237
	v_mul_f32_e32 v166, v166, v237
	v_mul_f32_e32 v167, v167, v237
	v_fma_f32 v164, v164, v16, v32
	v_fma_f32 v165, v165, v17, v33
	v_fma_f32 v166, v166, v18, v34
	v_fma_f32 v167, v167, v19, v35
	v_cvt_pk_bf16_f32 v164, v164, v165
	v_cvt_pk_bf16_f32 v165, v166, v167
	global_store_dwordx2 v106, v[164:165], s[22:23]
	v_mul_f32_e32 v168, v168, v237
	v_mul_f32_e32 v169, v169, v237
	v_mul_f32_e32 v170, v170, v237
	v_mul_f32_e32 v171, v171, v237
	v_fma_f32 v168, v168, v20, v36
	v_fma_f32 v169, v169, v21, v37
	v_fma_f32 v170, v170, v22, v38
	v_fma_f32 v171, v171, v23, v39
	v_cvt_pk_bf16_f32 v168, v168, v169
	v_cvt_pk_bf16_f32 v169, v170, v171
	global_store_dwordx2 v106, v[168:169], s[22:23] offset:512
	v_mul_f32_e32 v172, v172, v237
	v_mul_f32_e32 v173, v173, v237
	v_mul_f32_e32 v174, v174, v237
	v_mul_f32_e32 v175, v175, v237
	v_fma_f32 v172, v172, v24, v40
	v_fma_f32 v173, v173, v25, v41
	v_fma_f32 v174, v174, v26, v42
	v_fma_f32 v175, v175, v27, v43
	v_cvt_pk_bf16_f32 v172, v172, v173
	v_cvt_pk_bf16_f32 v173, v174, v175
	global_store_dwordx2 v106, v[172:173], s[22:23] offset:1024
	v_mul_f32_e32 v176, v176, v237
	v_mul_f32_e32 v177, v177, v237
	v_mul_f32_e32 v178, v178, v237
	v_mul_f32_e32 v179, v179, v237
	v_fma_f32 v176, v176, v28, v44
	v_fma_f32 v177, v177, v29, v45
	v_fma_f32 v178, v178, v30, v46
	v_fma_f32 v179, v179, v31, v47
	v_cvt_pk_bf16_f32 v176, v176, v177
	v_cvt_pk_bf16_f32 v177, v178, v179
	global_store_dwordx2 v106, v[176:177], s[22:23] offset:1536
	s_waitcnt vmcnt(28)
	v_mul_f32_e32 v250, v180, v180
	v_mul_f32_e32 v251, v182, v182
	v_fmac_f32_e32 v250, v181, v181
	v_fmac_f32_e32 v251, v183, v183
	v_add_f32_e32 v238, v250, v251
	v_mul_f32_e32 v250, v184, v184
	v_mul_f32_e32 v251, v186, v186
	v_fmac_f32_e32 v250, v185, v185
	v_fmac_f32_e32 v251, v187, v187
	v_add_f32_e32 v250, v250, v251
	v_add_f32_e32 v238, v238, v250
	v_mul_f32_e32 v250, v188, v188
	v_mul_f32_e32 v251, v190, v190
	v_fmac_f32_e32 v250, v189, v189
	v_fmac_f32_e32 v251, v191, v191
	v_add_f32_e32 v250, v250, v251
	v_add_f32_e32 v238, v238, v250
	v_mul_f32_e32 v250, v192, v192
	v_mul_f32_e32 v251, v194, v194
	v_fmac_f32_e32 v250, v193, v193
	v_fmac_f32_e32 v251, v195, v195
	v_add_f32_e32 v250, v250, v251
	v_add_f32_e32 v238, v238, v250
	s_waitcnt vmcnt(24)
	v_mul_f32_e32 v250, v86, v86
	v_mul_f32_e32 v251, v88, v88
	v_fmac_f32_e32 v250, v87, v87
	v_fmac_f32_e32 v251, v89, v89
	v_add_f32_e32 v239, v250, v251
	v_mul_f32_e32 v250, v90, v90
	v_mul_f32_e32 v251, v92, v92
	v_fmac_f32_e32 v250, v91, v91
	v_fmac_f32_e32 v251, v93, v93
	v_add_f32_e32 v250, v250, v251
	v_add_f32_e32 v239, v239, v250
	v_mul_f32_e32 v250, v94, v94
	v_mul_f32_e32 v251, v96, v96
	v_fmac_f32_e32 v250, v95, v95
	v_fmac_f32_e32 v251, v97, v97
	v_add_f32_e32 v250, v250, v251
	v_add_f32_e32 v239, v239, v250
	v_mul_f32_e32 v250, v98, v98
	v_mul_f32_e32 v251, v100, v100
	v_fmac_f32_e32 v250, v99, v99
	v_fmac_f32_e32 v251, v101, v101
	v_add_f32_e32 v250, v250, v251
	v_add_f32_e32 v239, v239, v250
	s_waitcnt vmcnt(20)
	v_mul_f32_e32 v250, v218, v218
	v_mul_f32_e32 v251, v220, v220
	v_fmac_f32_e32 v250, v219, v219
	v_fmac_f32_e32 v251, v221, v221
	v_add_f32_e32 v240, v250, v251
	v_mul_f32_e32 v250, v222, v222
	v_mul_f32_e32 v251, v224, v224
	v_fmac_f32_e32 v250, v223, v223
	v_fmac_f32_e32 v251, v225, v225
	v_add_f32_e32 v250, v250, v251
	v_add_f32_e32 v240, v240, v250
	v_mul_f32_e32 v250, v226, v226
	v_mul_f32_e32 v251, v228, v228
	v_fmac_f32_e32 v250, v227, v227
	v_fmac_f32_e32 v251, v229, v229
	v_add_f32_e32 v250, v250, v251
	v_add_f32_e32 v240, v240, v250
	v_mul_f32_e32 v250, v230, v230
	v_mul_f32_e32 v251, v232, v232
	v_fmac_f32_e32 v250, v231, v231
	v_fmac_f32_e32 v251, v233, v233
	v_add_f32_e32 v250, v250, v251
	v_add_f32_e32 v240, v240, v250
	s_waitcnt vmcnt(16)
; __device__ __forceinline__ unsigned pk2(float lo, float hi) { f32x2_t v = {lo, hi}; bf16x2_t b = __builtin_convertvector(v, bf16x2_t); return __builtin_bit_cast(unsigned, b); }
; __device__ __forceinline__ void norm_mod_phase(const float* X, const float* ng, const float* mod, bf16* H, int G) {
;     ...
;             for (int r = 0; r < 4; ++r) { float q = 0.f;
; #pragma unroll
;                 for (int j = 0; j < 4; ++j) q += (v[r][j].x * v[r][j].x + v[r][j].y * v[r][j].y) + (v[r][j].z * v[r][j].z + v[r][j].w * v[r][j].w);
;                 s[r] = q; }
; #pragma unroll
;             for (int o = 1; o < 64; o <<= 1) {
; #pragma unroll
;                 for (int r = 0; r < 4; ++r) s[r] += __shfl_xor(s[r], o); }
; #pragma unroll
;             for (int r = 0; r < 4; ++r) { if (!has[r]) continue;
;                 const float rs = __builtin_amdgcn_rsqf(s[r] * (1.f / D) + EPSN); v2u* o8 = (v2u*)(H + (size_t)mr[r] * D) + lane;
; #pragma unroll
;                 for (int j = 0; j < 4; ++j) { const f32x4 h = v[r][j] * rs * gs[j] + sh[j]; o8[64 * j] = (v2u){pk2(h.x, h.y), pk2(h.z, h.w)}; } }
	v_mul_f32_e32 v250, v196, v196
	v_mul_f32_e32 v251, v198, v198
	v_fmac_f32_e32 v250, v197, v197
	v_fmac_f32_e32 v251, v199, v199
	v_add_f32_e32 v241, v250, v251
	v_mul_f32_e32 v250, v200, v200
	v_mul_f32_e32 v251, v202, v202
	v_fmac_f32_e32 v250, v201, v201
	v_fmac_f32_e32 v251, v203, v203
	v_add_f32_e32 v250, v250, v251
	v_add_f32_e32 v241, v241, v250
	v_mul_f32_e32 v250, v204, v204
	v_mul_f32_e32 v251, v206, v206
	v_fmac_f32_e32 v250, v205, v205
	v_fmac_f32_e32 v251, v207, v207
	v_add_f32_e32 v250, v250, v251
	v_add_f32_e32 v241, v241, v250
	v_mul_f32_e32 v250, v102, v102
	v_mul_f32_e32 v251, v104, v104
	v_fmac_f32_e32 v250, v103, v103
	v_fmac_f32_e32 v251, v105, v105
	v_add_f32_e32 v250, v250, v251
	v_add_f32_e32 v241, v241, v250
	s_nop 1
	v_add_f32_dpp v238, v238, v238 quad_perm:[1,0,3,2] row_mask:0xf bank_mask:0xf
	v_add_f32_dpp v239, v239, v239 quad_perm:[1,0,3,2] row_mask:0xf bank_mask:0xf
	v_add_f32_dpp v240, v240, v240 quad_perm:[1,0,3,2] row_mask:0xf bank_mask:0xf
	v_add_f32_dpp v241, v241, v241 quad_perm:[1,0,3,2] row_mask:0xf bank_mask:0xf
	v_add_f32_dpp v238, v238, v238 quad_perm:[2,3,0,1] row_mask:0xf bank_mask:0xf
	v_add_f32_dpp v239, v239, v239 quad_perm:[2,3,0,1] row_mask:0xf bank_mask:0xf
	v_add_f32_dpp v240, v240, v240 quad_perm:[2,3,0,1] row_mask:0xf bank_mask:0xf
	v_add_f32_dpp v241, v241, v241 quad_perm:[2,3,0,1] row_mask:0xf bank_mask:0xf
	v_add_f32_dpp v238, v238, v238 row_half_mirror row_mask:0xf bank_mask:0xf
	v_add_f32_dpp v239, v239, v239 row_half_mirror row_mask:0xf bank_mask:0xf
	v_add_f32_dpp v240, v240, v240 row_half_mirror row_mask:0xf bank_mask:0xf
	v_add_f32_dpp v241, v241, v241 row_half_mirror row_mask:0xf bank_mask:0xf
	v_add_f32_dpp v238, v238, v238 row_mirror row_mask:0xf bank_mask:0xf
	v_add_f32_dpp v239, v239, v239 row_mirror row_mask:0xf bank_mask:0xf
	v_add_f32_dpp v240, v240, v240 row_mirror row_mask:0xf bank_mask:0xf
	v_add_f32_dpp v241, v241, v241 row_mirror row_mask:0xf bank_mask:0xf
	v_mov_b32_e32 v109, v238
	v_mov_b32_e32 v110, v239
	v_mov_b32_e32 v111, v240
	v_mov_b32_e32 v112, v241
	s_nop 1
	v_permlane16_swap_b32_e32 v109, v238
	v_permlane16_swap_b32_e32 v110, v239
	v_permlane16_swap_b32_e32 v111, v240
	v_permlane16_swap_b32_e32 v112, v241
	s_nop 1
	v_add_f32_e32 v238, v238, v109
	v_add_f32_e32 v239, v239, v110
	v_add_f32_e32 v240, v240, v111
	v_add_f32_e32 v241, v241, v112
	v_mov_b32_e32 v109, v238
	v_mov_b32_e32 v110, v239
	v_mov_b32_e32 v111, v240
	v_mov_b32_e32 v112, v241
	s_nop 1
	v_permlane32_swap_b32_e32 v109, v238
	v_permlane32_swap_b32_e32 v110, v239
	v_permlane32_swap_b32_e32 v111, v240
	v_permlane32_swap_b32_e32 v112, v241
	s_nop 1
	v_add_f32_e32 v238, v238, v109
	v_add_f32_e32 v239, v239, v110
	v_add_f32_e32 v240, v240, v111
	v_add_f32_e32 v241, v241, v112
	v_fmamk_f32 v238, v238, 0x3a800000, v108
	v_fmamk_f32 v239, v239, 0x3a800000, v108
	v_fmamk_f32 v240, v240, 0x3a800000, v108
	v_fmamk_f32 v241, v241, 0x3a800000, v108
	v_rsq_f32_e32 v238, v238
	v_rsq_f32_e32 v239, v239
	v_rsq_f32_e32 v240, v240
	v_rsq_f32_e32 v241, v241
	s_nop 0
	s_add_i32 s18, s16, 8192
	s_lshl_b32 s20, s18, 11
	s_add_u32 s22, s12, s20
	s_addc_u32 s23, s13, 0
	v_mul_f32_e32 v180, v180, v238
	v_mul_f32_e32 v181, v181, v238
	v_mul_f32_e32 v182, v182, v238
	v_mul_f32_e32 v183, v183, v238
	v_fma_f32 v180, v180, v48, v64
	v_fma_f32 v181, v181, v49, v65
	v_fma_f32 v182, v182, v50, v66
	v_fma_f32 v183, v183, v51, v67
	v_cvt_pk_bf16_f32 v180, v180, v181
	v_cvt_pk_bf16_f32 v181, v182, v183
	global_store_dwordx2 v106, v[180:181], s[22:23]
	v_mul_f32_e32 v184, v184, v238
	v_mul_f32_e32 v185, v185, v238
	v_mul_f32_e32 v186, v186, v238
	v_mul_f32_e32 v187, v187, v238
	v_fma_f32 v184, v184, v52, v68
	v_fma_f32 v185, v185, v53, v69
	v_fma_f32 v186, v186, v54, v70
	v_fma_f32 v187, v187, v55, v71
	v_cvt_pk_bf16_f32 v184, v184, v185
	v_cvt_pk_bf16_f32 v185, v186, v187
	global_store_dwordx2 v106, v[184:185], s[22:23] offset:512
	v_mul_f32_e32 v188, v188, v238
	v_mul_f32_e32 v189, v189, v238
	v_mul_f32_e32 v190, v190, v238
	v_mul_f32_e32 v191, v191, v238
	v_fma_f32 v188, v188, v56, v72
	v_fma_f32 v189, v189, v57, v73
	v_fma_f32 v190, v190, v58, v74
	v_fma_f32 v191, v191, v59, v75
	v_cvt_pk_bf16_f32 v188, v188, v189
	v_cvt_pk_bf16_f32 v189, v190, v191
	global_store_dwordx2 v106, v[188:189], s[22:23] offset:1024
	v_mul_f32_e32 v192, v192, v238
	v_mul_f32_e32 v193, v193, v238
	v_mul_f32_e32 v194, v194, v238
	v_mul_f32_e32 v195, v195, v238
	v_fma_f32 v192, v192, v60, v76
	v_fma_f32 v193, v193, v61, v77
	v_fma_f32 v194, v194, v62, v78
	v_fma_f32 v195, v195, v63, v79
	v_cvt_pk_bf16_f32 v192, v192, v193
	v_cvt_pk_bf16_f32 v193, v194, v195
	global_store_dwordx2 v106, v[192:193], s[22:23] offset:1536
	s_add_i32 s18, s18, s14
	s_lshl_b32 s20, s18, 11
	s_add_u32 s22, s12, s20
; __device__ __forceinline__ unsigned pk2(float lo, float hi) { f32x2_t v = {lo, hi}; bf16x2_t b = __builtin_convertvector(v, bf16x2_t); return __builtin_bit_cast(unsigned, b); }
; __device__ __forceinline__ void norm_mod_phase(const float* X, const float* ng, const float* mod, bf16* H, int G) {
;     ...
;             for (int r = 0; r < 4; ++r) { if (!has[r]) continue;
;                 const float rs = __builtin_amdgcn_rsqf(s[r] * (1.f / D) + EPSN); v2u* o8 = (v2u*)(H + (size_t)mr[r] * D) + lane;
; #pragma unroll
;                 for (int j = 0; j < 4; ++j) { const f32x4 h = v[r][j] * rs * gs[j] + sh[j]; o8[64 * j] = (v2u){pk2(h.x, h.y), pk2(h.z, h.w)}; } }
	s_addc_u32 s23, s13, 0
	v_mul_f32_e32 v86, v86, v239
	v_mul_f32_e32 v87, v87, v239
	v_mul_f32_e32 v88, v88, v239
	v_mul_f32_e32 v89, v89, v239
	v_fma_f32 v86, v86, v48, v64
	v_fma_f32 v87, v87, v49, v65
	v_fma_f32 v88, v88, v50, v66
	v_fma_f32 v89, v89, v51, v67
	v_cvt_pk_bf16_f32 v86, v86, v87
	v_cvt_pk_bf16_f32 v87, v88, v89
	global_store_dwordx2 v106, v[86:87], s[22:23]
	v_mul_f32_e32 v90, v90, v239
	v_mul_f32_e32 v91, v91, v239
	v_mul_f32_e32 v92, v92, v239
	v_mul_f32_e32 v93, v93, v239
	v_fma_f32 v90, v90, v52, v68
	v_fma_f32 v91, v91, v53, v69
	v_fma_f32 v92, v92, v54, v70
	v_fma_f32 v93, v93, v55, v71
	v_cvt_pk_bf16_f32 v90, v90, v91
	v_cvt_pk_bf16_f32 v91, v92, v93
	global_store_dwordx2 v106, v[90:91], s[22:23] offset:512
	v_mul_f32_e32 v94, v94, v239
	v_mul_f32_e32 v95, v95, v239
	v_mul_f32_e32 v96, v96, v239
	v_mul_f32_e32 v97, v97, v239
	v_fma_f32 v94, v94, v56, v72
	v_fma_f32 v95, v95, v57, v73
	v_fma_f32 v96, v96, v58, v74
	v_fma_f32 v97, v97, v59, v75
	v_cvt_pk_bf16_f32 v94, v94, v95
	v_cvt_pk_bf16_f32 v95, v96, v97
	global_store_dwordx2 v106, v[94:95], s[22:23] offset:1024
	v_mul_f32_e32 v98, v98, v239
	v_mul_f32_e32 v99, v99, v239
	v_mul_f32_e32 v100, v100, v239
	v_mul_f32_e32 v101, v101, v239
	v_fma_f32 v98, v98, v60, v76
	v_fma_f32 v99, v99, v61, v77
	v_fma_f32 v100, v100, v62, v78
	v_fma_f32 v101, v101, v63, v79
	v_cvt_pk_bf16_f32 v98, v98, v99
	v_cvt_pk_bf16_f32 v99, v100, v101
	global_store_dwordx2 v106, v[98:99], s[22:23] offset:1536
	s_add_i32 s18, s18, s14
	s_lshl_b32 s20, s18, 11
	s_add_u32 s22, s12, s20
	s_addc_u32 s23, s13, 0
	v_mul_f32_e32 v218, v218, v240
	v_mul_f32_e32 v219, v219, v240
	v_mul_f32_e32 v220, v220, v240
	v_mul_f32_e32 v221, v221, v240
	v_fma_f32 v218, v218, v48, v64
	v_fma_f32 v219, v219, v49, v65
	v_fma_f32 v220, v220, v50, v66
	v_fma_f32 v221, v221, v51, v67
	v_cvt_pk_bf16_f32 v218, v218, v219
	v_cvt_pk_bf16_f32 v219, v220, v221
	global_store_dwordx2 v106, v[218:219], s[22:23]
	v_mul_f32_e32 v222, v222, v240
	v_mul_f32_e32 v223, v223, v240
	v_mul_f32_e32 v224, v224, v240
	v_mul_f32_e32 v225, v225, v240
	v_fma_f32 v222, v222, v52, v68
	v_fma_f32 v223, v223, v53, v69
	v_fma_f32 v224, v224, v54, v70
	v_fma_f32 v225, v225, v55, v71
	v_cvt_pk_bf16_f32 v222, v222, v223
	v_cvt_pk_bf16_f32 v223, v224, v225
	global_store_dwordx2 v106, v[222:223], s[22:23] offset:512
	v_mul_f32_e32 v226, v226, v240
	v_mul_f32_e32 v227, v227, v240
	v_mul_f32_e32 v228, v228, v240
	v_mul_f32_e32 v229, v229, v240
	v_fma_f32 v226, v226, v56, v72
	v_fma_f32 v227, v227, v57, v73
	v_fma_f32 v228, v228, v58, v74
	v_fma_f32 v229, v229, v59, v75
	v_cvt_pk_bf16_f32 v226, v226, v227
	v_cvt_pk_bf16_f32 v227, v228, v229
	global_store_dwordx2 v106, v[226:227], s[22:23] offset:1024
	v_mul_f32_e32 v230, v230, v240
	v_mul_f32_e32 v231, v231, v240
	v_mul_f32_e32 v232, v232, v240
	v_mul_f32_e32 v233, v233, v240
	v_fma_f32 v230, v230, v60, v76
	v_fma_f32 v231, v231, v61, v77
	v_fma_f32 v232, v232, v62, v78
	v_fma_f32 v233, v233, v63, v79
	v_cvt_pk_bf16_f32 v230, v230, v231
	v_cvt_pk_bf16_f32 v231, v232, v233
	global_store_dwordx2 v106, v[230:231], s[22:23] offset:1536
	s_add_i32 s18, s18, s14
	s_lshl_b32 s20, s18, 11
	s_add_u32 s22, s12, s20
	s_addc_u32 s23, s13, 0
	v_mul_f32_e32 v196, v196, v241
	v_mul_f32_e32 v197, v197, v241
	v_mul_f32_e32 v198, v198, v241
	v_mul_f32_e32 v199, v199, v241
	v_fma_f32 v196, v196, v48, v64
	v_fma_f32 v197, v197, v49, v65
	v_fma_f32 v198, v198, v50, v66
	v_fma_f32 v199, v199, v51, v67
	v_cvt_pk_bf16_f32 v196, v196, v197
	v_cvt_pk_bf16_f32 v197, v198, v199
	global_store_dwordx2 v106, v[196:197], s[22:23]
	v_mul_f32_e32 v200, v200, v241
	v_mul_f32_e32 v201, v201, v241
	v_mul_f32_e32 v202, v202, v241
	v_mul_f32_e32 v203, v203, v241
	v_fma_f32 v200, v200, v52, v68
	v_fma_f32 v201, v201, v53, v69
	v_fma_f32 v202, v202, v54, v70
	v_fma_f32 v203, v203, v55, v71
	v_cvt_pk_bf16_f32 v200, v200, v201
	v_cvt_pk_bf16_f32 v201, v202, v203
	global_store_dwordx2 v106, v[200:201], s[22:23] offset:512
	v_mul_f32_e32 v204, v204, v241
	v_mul_f32_e32 v205, v205, v241
	v_mul_f32_e32 v206, v206, v241
	v_mul_f32_e32 v207, v207, v241
	v_fma_f32 v204, v204, v56, v72
	v_fma_f32 v205, v205, v57, v73
	v_fma_f32 v206, v206, v58, v74
	v_fma_f32 v207, v207, v59, v75
	v_cvt_pk_bf16_f32 v204, v204, v205
	v_cvt_pk_bf16_f32 v205, v206, v207
	global_store_dwordx2 v106, v[204:205], s[22:23] offset:1024
	v_mul_f32_e32 v102, v102, v241
	v_mul_f32_e32 v103, v103, v241
	v_mul_f32_e32 v104, v104, v241
	v_mul_f32_e32 v105, v105, v241
	v_fma_f32 v102, v102, v60, v76
	v_fma_f32 v103, v103, v61, v77
	v_fma_f32 v104, v104, v62, v78
	v_fma_f32 v105, v105, v63, v79
	v_cvt_pk_bf16_f32 v102, v102, v103
	v_cvt_pk_bf16_f32 v103, v104, v105
	global_store_dwordx2 v106, v[102:103], s[22:23] offset:1536
	s_branch .LBB0_96
